# chain workgroups start their L2 write-back (not waited for) in the middle of the last chunk, so the arrival-time write-back at the P2 barrier is nearly empty
# baseline (speedup 1.0000x reference)
; #define LAS __attribute__((address_space(3)))
; __device__ __forceinline__ f32x4 mfma16(h16x8 a, h16x8 b, f32x4 c) { return __builtin_amdgcn_mfma_f32_16x16x32_f16(a, b, c, 0, 0, 0); }
; __device__ __forceinline__ float sigm(float x) { return __builtin_amdgcn_rcpf(1.f + __expf(-x)); }
; __device__ __forceinline__ void mlstm_chain(const Params& p, LAS unsigned char* lds, const MlChain ch) {
;     ...
;         {
;             const int tt = wave & 3, vp = wave >> 2, t = tt * 16 + fr;
;             h16x8 pa[2], qa[2];
; #pragma unroll
;             for (int ks = 0; ks < 2; ++ks) { pa[ks] = *(const LAS h16x8*)(PP + t * 72 + ks * 32 + fq * 8); qa[ks] = *(const LAS h16x8*)(QS + t * 72 + ks * 32 + fq * 8); }
;             const float mxt = fmaxf(mcur, CCM[c * 64 + t]);
;             const float sc = __expf(mcur - mxt);
;             const float den = DEN[t] + DEN[64 + t] + sc * DQN[t];
;             const float inv = __builtin_amdgcn_rcpf(fmaxf(fabsf(den), __expf(-(CBC[c * 64 + t] + mxt))));
;             float hv[2][4], ssq = 0.f;
; #pragma unroll
;             for (int j = 0; j < 2; ++j) {
;                 const int vt = vp * 2 + j;
;                 f32x4 a1 = {0.f, 0.f, 0.f, 0.f}, a2 = {0.f, 0.f, 0.f, 0.f};
; #pragma unroll
;                 for (int ks = 0; ks < 2; ++ks) {
;                     const h16x8 vb = *(const LAS h16x8*)(VT + (vt * 16 + fr) * 72 + ks * 32 + fq * 8);
;                     const h16x8 cbf = *(const LAS h16x8*)(CT + (vt * 16 + fr) * 72 + ks * 32 + fq * 8);
;                     a1 = mfma16(vb, pa[ks], a1); a2 = mfma16(cbf, qa[ks], a2);
;                 }
;                 const h16x4 o4 = j == 0 ? oc0 : oc1;
; #pragma unroll
;                 for (int r = 0; r < 4; ++r) { const float hh = (a1[r] + sc * a2[r]) * inv * sigm((float)o4[r]); hv[j][r] = hh; ssq += hh * hh; }
;             }
;             ssq += __shfl_xor(ssq, 16); ssq += __shfl_xor(ssq, 32);
;             if (fq == 0) SSQ[vp * 64 + t] = ssq;
.LBB0_278:
	s_or_b64 exec, exec, s[0:1]
	v_lshl_add_u32 v8, v163, 2, 0
	s_waitcnt lgkmcnt(0)
	s_barrier
	s_waitcnt lgkmcnt(0)
	v_add_u32_e32 v9, 0x18500, v8
	ds_read_b32 v9, v9
	ds_read_b128 v[10:13], v171 offset:55296
	v_add_u32_e32 v8, 0x14500, v8
	ds_read_b128 v[18:21], v171 offset:18496
	ds_read_b32 v8, v8
	s_waitcnt lgkmcnt(3)
	v_max_f32_e32 v9, v9, v9
	v_max_f32_e32 v9, v16, v9
	v_sub_f32_e32 v14, v181, v9
	v_mul_f32_e32 v14, 0x3fb8aa3b, v14
	v_exp_f32_e32 v46, v14
	ds_read_b32 v30, v165
	ds_read_b32 v31, v166
	ds_read_b32 v32, v167
	ds_read_b128 v[14:17], v164 offset:36864
	ds_read_b128 v[22:25], v171 offset:18432
	ds_read_b128 v[26:29], v171 offset:55360
	s_waitcnt lgkmcnt(4)
	v_add_f32_e32 v42, v30, v31
	v_add_f32_e32 v8, v9, v8
	s_waitcnt lgkmcnt(3)
	v_fmac_f32_e32 v42, v32, v46
	ds_read_b128 v[30:33], v164 offset:64512
	v_mul_f32_e32 v8, 0xbfb8aa3b, v8
	v_exp_f32_e32 v8, v8
	ds_read_b128 v[38:41], v164 offset:36928
	ds_read_b128 v[60:63], v164 offset:39168
	ds_read_b128 v[56:59], v164 offset:64576
	v_max_f32_e64 v8, |v42|, v8
	v_rcp_f32_e32 v64, v8
	s_waitcnt vmcnt(3)
	v_cvt_f32_f16_e32 v8, v104
	v_cvt_f32_f16_sdwa v9, v104 dst_sel:DWORD dst_unused:UNUSED_PAD src0_sel:WORD_1
	s_waitcnt lgkmcnt(6)
	v_mfma_f32_16x16x32_f16 v[14:17], v[14:17], v[10:13], 0
	ds_read_b128 v[42:45], v164 offset:39232
	v_mul_f32_e32 v8, 0xbfb8aa3b, v8
	v_mul_f32_e32 v9, 0xbfb8aa3b, v9
	s_waitcnt lgkmcnt(4)
	v_mfma_f32_16x16x32_f16 v[30:33], v[30:33], v[22:25], 0
	v_exp_f32_e32 v8, v8
	v_exp_f32_e32 v9, v9
	ds_read_b128 v[34:37], v147 offset:64
	s_waitcnt lgkmcnt(4)
	v_mfma_f32_16x16x32_f16 v[14:17], v[38:41], v[26:29], v[14:17]
	v_add_f32_e32 v8, 1.0, v8
	v_add_f32_e32 v9, 1.0, v9
	v_rcp_f32_e32 v8, v8
	s_waitcnt lgkmcnt(2)
	v_mfma_f32_16x16x32_f16 v[30:33], v[56:59], v[18:21], v[30:33]
	v_rcp_f32_e32 v9, v9
	ds_read_b128 v[38:41], v147
	v_mfma_f32_16x16x32_f16 v[56:59], v[60:63], v[10:13], 0
	s_nop 4
	v_fma_f32 v14, v46, v30, v14
	v_fma_f32 v15, v46, v31, v15
	v_cvt_f32_f16_e32 v30, v105
	v_cvt_f32_f16_sdwa v31, v105 dst_sel:DWORD dst_unused:UNUSED_PAD src0_sel:WORD_1
	v_pk_mul_f32 v[14:15], v[64:65], v[14:15] op_sel_hi:[0,1]
	v_pk_mul_f32 v[8:9], v[8:9], v[14:15]
	v_mul_f32_e32 v14, 0xbfb8aa3b, v30
	v_mul_f32_e32 v15, 0xbfb8aa3b, v31
	v_exp_f32_e32 v14, v14
	v_exp_f32_e32 v15, v15
	v_pk_fma_f32 v[10:11], v[46:47], v[32:33], v[16:17] op_sel_hi:[0,1,1]
	v_pk_mul_f32 v[10:11], v[64:65], v[10:11] op_sel_hi:[0,1]
	v_add_f32_e32 v14, 1.0, v14
	v_add_f32_e32 v15, 1.0, v15
	v_rcp_f32_e32 v14, v14
	v_rcp_f32_e32 v15, v15
	s_waitcnt vmcnt(2)
	v_readfirstlane_b32 s97, v132
	s_cmp_lt_u32 s97, 64
	s_cbranch_scc0 .Lewb_skip
	buffer_wbl2 sc1
.Lewb_skip:
	v_cvt_f32_f16_e32 v32, v102
	v_cvt_f32_f16_sdwa v33, v102 dst_sel:DWORD dst_unused:UNUSED_PAD src0_sel:WORD_1
	v_pk_mul_f32 v[30:31], v[8:9], v[8:9]
	v_pk_mul_f32 v[12:13], v[14:15], v[10:11]
	s_waitcnt lgkmcnt(0)
	v_mfma_f32_16x16x32_f16 v[14:17], v[38:41], v[22:25], 0
	v_mul_f32_e64 v10, v12, v12
	v_mul_f32_e64 v11, v13, v13
	v_mfma_f32_16x16x32_f16 v[22:25], v[42:45], v[26:29], v[56:59]
	v_mul_f32_e32 v26, 0xbfb8aa3b, v32
	v_mul_f32_e32 v27, 0xbfb8aa3b, v33
	v_exp_f32_e32 v26, v26
	v_exp_f32_e32 v27, v27
	v_mfma_f32_16x16x32_f16 v[16:19], v[34:37], v[18:21], v[14:17]
	v_cvt_f32_f16_e32 v20, v103
	v_cvt_f32_f16_sdwa v21, v103 dst_sel:DWORD dst_unused:UNUSED_PAD src0_sel:WORD_1
	v_mul_f32_e32 v20, 0xbfb8aa3b, v20
	v_add_f32_e32 v14, 1.0, v26
	v_add_f32_e32 v15, 1.0, v27
	v_mul_f32_e32 v21, 0xbfb8aa3b, v21
	v_rcp_f32_e32 v14, v14
	v_rcp_f32_e32 v15, v15
	v_exp_f32_e32 v20, v20
	v_exp_f32_e32 v21, v21
	v_pk_fma_f32 v[16:17], v[46:47], v[16:17], v[22:23] op_sel_hi:[0,1,1]
	v_pk_mul_f32 v[16:17], v[64:65], v[16:17] op_sel_hi:[0,1]
	v_pk_mul_f32 v[16:17], v[14:15], v[16:17]
	v_add_f32_e32 v14, 1.0, v20
	v_add_f32_e32 v15, 1.0, v21
	v_rcp_f32_e32 v14, v14
	v_rcp_f32_e32 v15, v15
	v_add_f32_e32 v22, v30, v31
	v_pk_fma_f32 v[18:19], v[46:47], v[18:19], v[24:25] op_sel_hi:[0,1,1]
	v_add_f32_e32 v10, v10, v22
	v_pk_mul_f32 v[20:21], v[16:17], v[16:17]
	v_pk_mul_f32 v[18:19], v[64:65], v[18:19] op_sel_hi:[0,1]
	v_add_f32_e32 v10, v11, v10
	v_pk_mul_f32 v[14:15], v[14:15], v[18:19]
	v_add_f32_e32 v10, v10, v20
	v_pk_mul_f32 v[18:19], v[14:15], v[14:15]
	v_add_f32_e32 v10, v21, v10
	v_add_f32_e32 v10, v18, v10
	v_add_f32_e32 v10, v19, v10
	v_mov_b32_e32 v11, v10
	s_nop 1
	v_permlane16_swap_b32 v10, v11
	s_waitcnt lgkmcnt(0)
	v_add_f32_e32 v10, v10, v11
	v_mov_b32_e32 v11, v10
	s_nop 1
	v_permlane32_swap_b32 v10, v11
	s_and_saveexec_b64 s[0:1], vcc
	s_cbranch_execz .LBB0_280
	s_waitcnt lgkmcnt(0)
	v_add_f32_e32 v10, v10, v11
	v_add_u32_e32 v11, v160, v161
	ds_write_b32 v11, v10
